# v12: + DA query fragments kept in registers for the whole K/V loop (no LDS round trip per tile), s_setprio 1 inside the GEMM K-loops
# speedup vs baseline: 1.0519x; 1.0026x over previous
; DI int tidx() { int t = threadIdx.x; asm volatile("" : "+v"(t)); return t; }
; #define GAS __attribute__((address_space(1)))
; DI void gemm_stage(const u16* __restrict__ A, int lda, const u16* __restrict__ B, int ldb, int kt, char* sbuf) {
;   const int tid = tidx(), lane = tid & 63, wave = __builtin_amdgcn_readfirstlane(tid >> 6);
;   const int pp = lane >> 4, pos = lane & 15;
; #pragma unroll
;   for (int i = 0; i < 4; i++) {
;     const int blk = i * 4 + wave;
;     const int p = blk * 4 + pp;
;     const int row = 2 * p + (pos >> 3), c8 = (pos & 7) ^ (p & 7);
;     const u16* ga = A + (size_t)row * lda + kt * 64 + c8 * 8;
;     const u16* gb = B + (size_t)row * ldb + kt * 64 + c8 * 8;
;     __builtin_amdgcn_global_load_lds((const GAS void*)ga, (__attribute__((address_space(3))) void*)(sbuf + blk * 1024), 16, 0, 0);
;     __builtin_amdgcn_global_load_lds((const GAS void*)gb, (__attribute__((address_space(3))) void*)(sbuf + 16384 + blk * 1024), 16, 0, 0);
;   }
.LBB0_681:
	s_setprio 1
	s_mov_b32 s11, 0
	s_mov_b32 s31, 0
	v_readfirstlane_b32 s33, v202
	v_bfe_u32 v238, v202, 4, 2
	v_bfe_u32 v239, v202, 3, 1
	s_ashr_i32 s33, s33, 6
	s_lshl_b32 s13, s33, 3
	v_lshlrev_b32_e32 v122, 1, v238
	v_or3_b32 v122, s13, v122, v239
	v_lshl_or_b32 v238, s33, 2, v238
	v_bitop3_b32 v238, v238, 7, v202 bitop3:0x48
	v_lshlrev_b32_e32 v238, 4, v238
	v_mul_u32_u24_e32 v122, 0x800, v122
	v_add_u32_e32 v238, v122, v238
	v_add_u32_e32 v239, 0x10000, v238
	s_lshl_b32 s33, s33, 10
	s_add_u32 s14, s6, 0x20000
	s_addc_u32 s15, s7, 0
	s_add_u32 s16, s8, 0x20000
	s_addc_u32 s17, s9, 0

; #define MFMA32(a, b, c) __builtin_amdgcn_mfma_f32_32x32x16_bf16((a), (b), (c), 0, 0, 0)
; DI void gemm_main(f32x16 (&acc)[2][2], const u16* __restrict__ A, int lda, const u16* __restrict__ B, int ldb, int K, u16* sm) {
;     ...
;     for (int ks = 0; ks < 4; ks++) {
;       const int ca = ((ks * 2 + hh) ^ xa) << 4, cb = ((ks * 2 + hh) ^ xb) << 4;
;       const bf16x8 fa0 = *(const bf16x8*)(st + baseA + ca);
;       const bf16x8 fa1 = *(const bf16x8*)(st + baseA + 4096 + ca);
;       const bf16x8 fb0 = *(const bf16x8*)(st + baseB + cb);
;       const bf16x8 fb1 = *(const bf16x8*)(st + baseB + 4096 + cb);
;       acc[0][0] = MFMA32(fa0, fb0, acc[0][0]); acc[0][1] = MFMA32(fa0, fb1, acc[0][1]);
;       acc[1][0] = MFMA32(fa1, fb0, acc[1][0]); acc[1][1] = MFMA32(fa1, fb1, acc[1][1]);
;     }
;     asm volatile("s_waitcnt vmcnt(0)" ::: "memory");
;     __syncthreads();
.Lkl0_last:
	v_add_u32_e32 v122, s11, v68
	v_add3_u32 v123, s11, v69, v66
	v_add_u32_e32 v114, v122, v102
	v_add_u32_e32 v118, v123, v102
	ds_read_b128 v[106:109], v114
	ds_read_b128 v[110:113], v118 offset:16384
	ds_read_b128 v[114:117], v114 offset:4096
	ds_read_b128 v[118:121], v118 offset:20480
	v_add_u32_e32 v248, v122, v103
	v_add_u32_e32 v252, v123, v103
	ds_read_b128 v[240:243], v248
	ds_read_b128 v[244:247], v252 offset:16384
	ds_read_b128 v[248:251], v248 offset:4096
	ds_read_b128 v[252:255], v252 offset:20480
	s_waitcnt lgkmcnt(4)
	v_mfma_f32_32x32x16_bf16 v[18:33], v[114:117], v[110:113], v[18:33]
	v_mfma_f32_32x32x16_bf16 v[2:17], v[114:117], v[118:121], v[2:17]
	v_mfma_f32_32x32x16_bf16 v[50:65], v[106:109], v[110:113], v[50:65]
	v_mfma_f32_32x32x16_bf16 v[34:49], v[106:109], v[118:121], v[34:49]
	v_add_u32_e32 v114, v122, v104
	v_add_u32_e32 v118, v123, v104
	ds_read_b128 v[106:109], v114
	ds_read_b128 v[110:113], v118 offset:16384
	ds_read_b128 v[114:117], v114 offset:4096
	ds_read_b128 v[118:121], v118 offset:20480
	s_waitcnt lgkmcnt(4)
	v_mfma_f32_32x32x16_bf16 v[18:33], v[248:251], v[244:247], v[18:33]
	v_mfma_f32_32x32x16_bf16 v[2:17], v[248:251], v[252:255], v[2:17]
	v_mfma_f32_32x32x16_bf16 v[50:65], v[240:243], v[244:247], v[50:65]
	v_mfma_f32_32x32x16_bf16 v[34:49], v[240:243], v[252:255], v[34:49]
	v_add_u32_e32 v248, v122, v105
	v_add_u32_e32 v252, v123, v105
	ds_read_b128 v[240:243], v248
	ds_read_b128 v[244:247], v252 offset:16384
	ds_read_b128 v[248:251], v248 offset:4096
	ds_read_b128 v[252:255], v252 offset:20480
	s_waitcnt lgkmcnt(4)
	v_mfma_f32_32x32x16_bf16 v[18:33], v[114:117], v[110:113], v[18:33]
	v_mfma_f32_32x32x16_bf16 v[2:17], v[114:117], v[118:121], v[2:17]
	v_mfma_f32_32x32x16_bf16 v[50:65], v[106:109], v[110:113], v[50:65]
	v_mfma_f32_32x32x16_bf16 v[34:49], v[106:109], v[118:121], v[34:49]
	s_add_i32 s31, s31, 1
	s_waitcnt vmcnt(0) lgkmcnt(0)
	s_barrier
	v_mfma_f32_32x32x16_bf16 v[50:65], v[240:243], v[244:247], v[50:65]
	v_mfma_f32_32x32x16_bf16 v[34:49], v[240:243], v[252:255], v[34:49]
	v_mfma_f32_32x32x16_bf16 v[18:33], v[248:251], v[244:247], v[18:33]
	v_mfma_f32_32x32x16_bf16 v[2:17], v[248:251], v[252:255], v[2:17]
	s_setprio 0
	s_branch .LBB0_685

; DI int tidx() { int t = threadIdx.x; asm volatile("" : "+v"(t)); return t; }
; #define GAS __attribute__((address_space(1)))
; DI void gemm_stage(const u16* __restrict__ A, int lda, const u16* __restrict__ B, int ldb, int kt, char* sbuf) {
;   const int tid = tidx(), lane = tid & 63, wave = __builtin_amdgcn_readfirstlane(tid >> 6);
;   const int pp = lane >> 4, pos = lane & 15;
; #pragma unroll
;   for (int i = 0; i < 4; i++) {
;     const int blk = i * 4 + wave;
;     const int p = blk * 4 + pp;
;     const int row = 2 * p + (pos >> 3), c8 = (pos & 7) ^ (p & 7);
;     const u16* ga = A + (size_t)row * lda + kt * 64 + c8 * 8;
;     const u16* gb = B + (size_t)row * ldb + kt * 64 + c8 * 8;
;     __builtin_amdgcn_global_load_lds((const GAS void*)ga, (__attribute__((address_space(3))) void*)(sbuf + blk * 1024), 16, 0, 0);
;     __builtin_amdgcn_global_load_lds((const GAS void*)gb, (__attribute__((address_space(3))) void*)(sbuf + 16384 + blk * 1024), 16, 0, 0);
;   }
.LBB0_1201:
	s_setprio 1
	s_mov_b32 s7, 0
	s_mov_b32 s33, 0
	v_readfirstlane_b32 s36, v202
	v_bfe_u32 v238, v202, 4, 2
	v_bfe_u32 v239, v202, 3, 1
	s_ashr_i32 s36, s36, 6
	s_lshl_b32 s15, s36, 3
	v_lshlrev_b32_e32 v80, 1, v238
	v_or3_b32 v80, s15, v80, v239
	v_lshl_or_b32 v238, s36, 2, v238
	v_bitop3_b32 v238, v238, 7, v202 bitop3:0x48
	v_lshlrev_b32_e32 v238, 4, v238
	v_mul_u32_u24_e32 v80, 0x800, v80
	v_add_u32_e32 v238, v80, v238
	v_add_u32_e32 v239, 0x10000, v238
	s_lshl_b32 s36, s36, 10
	s_add_u32 s12, s8, 0x20000
	s_addc_u32 s13, s9, 0
	s_add_u32 s34, s10, 0x20000
	s_addc_u32 s35, s11, 0

; #define MFMA32(a, b, c) __builtin_amdgcn_mfma_f32_32x32x16_bf16((a), (b), (c), 0, 0, 0)
; DI void gemm_main(f32x16 (&acc)[2][2], const u16* __restrict__ A, int lda, const u16* __restrict__ B, int ldb, int K, u16* sm) {
;     ...
;     for (int ks = 0; ks < 4; ks++) {
;       const int ca = ((ks * 2 + hh) ^ xa) << 4, cb = ((ks * 2 + hh) ^ xb) << 4;
;       const bf16x8 fa0 = *(const bf16x8*)(st + baseA + ca);
;       const bf16x8 fa1 = *(const bf16x8*)(st + baseA + 4096 + ca);
;       const bf16x8 fb0 = *(const bf16x8*)(st + baseB + cb);
;       const bf16x8 fb1 = *(const bf16x8*)(st + baseB + 4096 + cb);
;       acc[0][0] = MFMA32(fa0, fb0, acc[0][0]); acc[0][1] = MFMA32(fa0, fb1, acc[0][1]);
;       acc[1][0] = MFMA32(fa1, fb0, acc[1][0]); acc[1][1] = MFMA32(fa1, fb1, acc[1][1]);
;     }
;     asm volatile("s_waitcnt vmcnt(0)" ::: "memory");
;     __syncthreads();
.Lkl1_last:
	v_add_u32_e32 v80, s7, v74
	v_add3_u32 v102, s7, v75, v66
	v_add_u32_e32 v94, v80, v76
	v_add_u32_e32 v98, v102, v76
	ds_read_b128 v[86:89], v94
	ds_read_b128 v[90:93], v98 offset:16384
	ds_read_b128 v[94:97], v94 offset:4096
	ds_read_b128 v[98:101], v98 offset:20480
	v_add_u32_e32 v248, v80, v77
	v_add_u32_e32 v252, v102, v77
	ds_read_b128 v[240:243], v248
	ds_read_b128 v[244:247], v252 offset:16384
	ds_read_b128 v[248:251], v248 offset:4096
	ds_read_b128 v[252:255], v252 offset:20480
	s_waitcnt lgkmcnt(4)
	v_mfma_f32_32x32x16_bf16 v[34:49], v[94:97], v[90:93], v[34:49]
	v_mfma_f32_32x32x16_bf16 v[50:65], v[86:89], v[90:93], v[50:65]
	v_mfma_f32_32x32x16_bf16 v[18:33], v[86:89], v[98:101], v[18:33]
	v_mfma_f32_32x32x16_bf16 v[2:17], v[94:97], v[98:101], v[2:17]
	v_add_u32_e32 v94, v80, v78
	v_add_u32_e32 v98, v102, v78
	ds_read_b128 v[86:89], v94
	ds_read_b128 v[90:93], v98 offset:16384
	ds_read_b128 v[94:97], v94 offset:4096
	ds_read_b128 v[98:101], v98 offset:20480
	s_waitcnt lgkmcnt(4)
	v_mfma_f32_32x32x16_bf16 v[34:49], v[248:251], v[244:247], v[34:49]
	v_mfma_f32_32x32x16_bf16 v[50:65], v[240:243], v[244:247], v[50:65]
	v_mfma_f32_32x32x16_bf16 v[18:33], v[240:243], v[252:255], v[18:33]
	v_mfma_f32_32x32x16_bf16 v[2:17], v[248:251], v[252:255], v[2:17]
	v_add_u32_e32 v248, v80, v79
	v_add_u32_e32 v252, v102, v79
	ds_read_b128 v[240:243], v248
	ds_read_b128 v[244:247], v252 offset:16384
	ds_read_b128 v[248:251], v248 offset:4096
	ds_read_b128 v[252:255], v252 offset:20480
	s_waitcnt lgkmcnt(4)
	v_mfma_f32_32x32x16_bf16 v[34:49], v[94:97], v[90:93], v[34:49]
	v_mfma_f32_32x32x16_bf16 v[50:65], v[86:89], v[90:93], v[50:65]
	v_mfma_f32_32x32x16_bf16 v[18:33], v[86:89], v[98:101], v[18:33]
	v_mfma_f32_32x32x16_bf16 v[2:17], v[94:97], v[98:101], v[2:17]
	s_add_i32 s33, s33, 1
	s_waitcnt vmcnt(0) lgkmcnt(0)
	s_barrier
	v_mfma_f32_32x32x16_bf16 v[50:65], v[240:243], v[244:247], v[50:65]
	v_mfma_f32_32x32x16_bf16 v[18:33], v[240:243], v[252:255], v[18:33]
	v_mfma_f32_32x32x16_bf16 v[34:49], v[248:251], v[244:247], v[34:49]
	v_mfma_f32_32x32x16_bf16 v[2:17], v[248:251], v[252:255], v[2:17]
	s_setprio 0
	s_branch .LBB0_1205

; DI f32x16 zero16() { f32x16 z; for (int i = 0; i < 16; i++) z[i] = 0.f; return z; }
; #define DA_FETCH(T) { const int ktn_ = min((T), nkt - 1); \
;       _Pragma("unroll") for (int i = 0; i < 2; i++) rk[i] = *(const u32x4*)(Kbase + (size_t)(ktn_ * 64 + i * 32) * 64); \
;       _Pragma("unroll") for (int i = 0; i < 4; i++) rv[i] = *(const u32x4*)(Vbase + (size_t)ktn_ * 8192 + (size_t)(i * 32) * 64); }
; DI void da_item(const Params& P, int layer, int b, int h, int qt, char* mb, char* smem) {
;     ...
;   const int krow_l = tid >> 3, kch = (tid & 7) * 8;
; #pragma unroll 1
;   for (int c = 0; c < 2; c++) {
; #pragma unroll
;     for (int ks = 0; ks < 4; ks++) *(bf16x8*)(sQw + r * KS_ + ks * 16 + hh * 8) = *(const bf16x8*)(Qd + tokq * 512 + h * 128 + c * 64 + ks * 16 + hh * 8);
;     f32x16 o[4] = {zero16(), zero16(), zero16(), zero16()};
;     float m = -INFINITY, l = 0.f;
;     const u16* Kbase = Kd + ((size_t)(((b * 4 + h) * 2 + c)) * L_ + krow_l) * 64 + kch;
;     const u16* Vbase = Vt + ((size_t)((b * 4 + h) * 128) * 128 + krow_l) * 64 + kch;
;     u32x4 rk[2], rv[4];
; #pragma unroll
;     for (int i = 0; i < 2; i++) rk[i] = *(const u32x4*)(Kbase + (size_t)(i * 32) * 64);
; #pragma unroll
;     for (int i = 0; i < 4; i++) rv[i] = *(const u32x4*)(Vbase + (size_t)(i * 32) * 64);
;     ...
;     __syncthreads();
;     DA_STAGE(0)
;     DA_FETCH(1)
;     __syncthreads();
.LBB0_4117:
	s_lshl_b32 s10, s29, 7
	v_lshl_add_u64 v[16:17], v[146:147], 0, s[10:11]
	global_load_dwordx4 v[4:7], v[16:17], off
	global_load_dwordx4 v[8:11], v[16:17], off offset:32
	global_load_dwordx4 v[12:15], v[16:17], off offset:64
	s_nop 0
	global_load_dwordx4 v[16:19], v[16:17], off offset:96
	s_lshl_b32 s10, s29, 13
	s_or_b32 s10, s10, s22
	v_lshl_add_u64 v[20:21], s[10:11], 0, v[144:145]
	v_lshlrev_b64 v[20:21], 7, v[20:21]
	v_lshl_add_u64 v[182:183], v[148:149], 0, v[20:21]
	global_load_dwordx4 v[20:23], v[182:183], off
	v_add_co_u32_e32 v24, vcc, s35, v182
	v_lshl_add_u64 v[44:45], v[182:183], 0, s[24:25]
	s_nop 0
	v_addc_co_u32_e32 v25, vcc, 0, v183, vcc
	global_load_dwordx4 v[24:27], v[24:25], off
	s_nop 0
	global_load_dwordx4 v[28:31], v[150:151], off
	global_load_dwordx4 v[32:35], v[156:157], off
	global_load_dwordx4 v[36:39], v[158:159], off
	global_load_dwordx4 v[40:43], v[160:161], off
	v_lshl_add_u64 v[46:47], v[182:183], 0, s[26:27]
	v_add_u32_e32 v3, v213, v218
	s_xor_b64 s[28:29], s[4:5], -1
	v_mov_b32_e32 v226, 0xff800000
	v_mov_b32_e32 v225, 0
	s_movk_i32 s10, 0xbf
	v_mov_b32_e32 v224, v222
	s_mov_b32 s30, 0
	s_waitcnt vmcnt(9)
	ds_write_b128 v212, v[4:7] offset:54272
	s_waitcnt vmcnt(8)
	ds_write_b128 v212, v[8:11] offset:54304
	s_waitcnt vmcnt(7)
	ds_write_b128 v212, v[12:15] offset:54336
	s_waitcnt vmcnt(6)
	ds_write_b128 v212, v[16:19] offset:54368
	v_mov_b32_e32 v240, v4
	v_mov_b32_e32 v241, v5
	v_mov_b32_e32 v242, v6
	v_mov_b32_e32 v243, v7
	v_mov_b32_e32 v244, v8
	v_mov_b32_e32 v245, v9
	v_mov_b32_e32 v246, v10
	v_mov_b32_e32 v247, v11
	v_mov_b32_e32 v248, v12
	v_mov_b32_e32 v249, v13
	v_mov_b32_e32 v250, v14
	v_mov_b32_e32 v251, v15
	v_mov_b32_e32 v252, v16
	v_mov_b32_e32 v253, v17
	v_mov_b32_e32 v254, v18
	v_mov_b32_e32 v255, v19
	s_waitcnt lgkmcnt(0)
	s_barrier
	global_load_dwordx4 v[114:117], v[44:45], off
	global_load_dwordx4 v[118:121], v[46:47], off
	global_load_dwordx4 v[122:125], v[152:153], off
	global_load_dwordx4 v[126:129], v[162:163], off
	global_load_dwordx4 v[130:133], v[164:165], off
	global_load_dwordx4 v[134:137], v[166:167], off
	s_waitcnt vmcnt(11)
	ds_write_b128 v3, v[20:23]
	s_waitcnt vmcnt(10)
	ds_write_b128 v3, v[24:27] offset:4608
	v_add_u32_e32 v3, v213, v219
	v_add_u32_e32 v4, 0x4800, v3
	s_waitcnt vmcnt(9)
	ds_write2_b64 v4, v[28:29], v[30:31] offset1:1
	v_add_u32_e32 v4, 0x5900, v3
	s_waitcnt vmcnt(8)
	ds_write2_b64 v4, v[32:33], v[34:35] offset1:1
	v_add_u32_e32 v4, 0x6a00, v3
	v_add_u32_e32 v3, 0x7b00, v3
	v_mov_b32_e32 v16, v2
	v_mov_b32_e32 v17, v2
	s_waitcnt vmcnt(7)
	ds_write2_b64 v4, v[36:37], v[38:39] offset1:1
	s_waitcnt vmcnt(6)
	ds_write2_b64 v3, v[40:41], v[42:43] offset1:1
	v_mov_b32_e32 v3, v2
	v_mov_b32_e32 v4, v2
	v_mov_b32_e32 v5, v2
	v_mov_b32_e32 v6, v2
	v_mov_b32_e32 v7, v2
	v_mov_b32_e32 v8, v2
	v_mov_b32_e32 v9, v2
	v_mov_b32_e32 v10, v2
	v_mov_b32_e32 v11, v2
	v_mov_b32_e32 v12, v2
	v_mov_b32_e32 v13, v2
	v_mov_b32_e32 v14, v2
	v_mov_b32_e32 v15, v2
	v_mov_b64_e32 v[32:33], v[16:17]
	v_mov_b64_e32 v[48:49], v[16:17]
	v_mov_b64_e32 v[64:65], v[16:17]
	v_mov_b64_e32 v[80:81], v[16:17]
	v_mov_b64_e32 v[30:31], v[14:15]
	v_mov_b64_e32 v[28:29], v[12:13]
	v_mov_b64_e32 v[26:27], v[10:11]
	v_mov_b64_e32 v[24:25], v[8:9]
	v_mov_b64_e32 v[22:23], v[6:7]
	v_mov_b64_e32 v[20:21], v[4:5]
	v_mov_b64_e32 v[18:19], v[2:3]
	v_mov_b64_e32 v[46:47], v[14:15]
	v_mov_b64_e32 v[44:45], v[12:13]
	v_mov_b64_e32 v[42:43], v[10:11]
	v_mov_b64_e32 v[40:41], v[8:9]
	v_mov_b64_e32 v[38:39], v[6:7]
	v_mov_b64_e32 v[36:37], v[4:5]
	v_mov_b64_e32 v[34:35], v[2:3]
	v_mov_b64_e32 v[62:63], v[14:15]
	v_mov_b64_e32 v[60:61], v[12:13]
	v_mov_b64_e32 v[58:59], v[10:11]
	v_mov_b64_e32 v[56:57], v[8:9]
	v_mov_b64_e32 v[54:55], v[6:7]
	v_mov_b64_e32 v[52:53], v[4:5]
	v_mov_b64_e32 v[50:51], v[2:3]
	v_mov_b64_e32 v[78:79], v[14:15]
	v_mov_b64_e32 v[76:77], v[12:13]
	v_mov_b64_e32 v[74:75], v[10:11]
	v_mov_b64_e32 v[72:73], v[8:9]
	v_mov_b64_e32 v[70:71], v[6:7]
	v_mov_b64_e32 v[68:69], v[4:5]
	v_mov_b64_e32 v[66:67], v[2:3]
	s_waitcnt lgkmcnt(0)
	s_barrier
	s_add_i32 s42, s30, 1
	s_cmp_ge_u32 s42, s40
	s_cbranch_scc1 .LBB0_4120
	s_branch .LBB0_4119

; #define MFMA32(a, b, c) __builtin_amdgcn_mfma_f32_32x32x16_bf16((a), (b), (c), 0, 0, 0)
; DI int crow(int i, int hh) { return (i & 3) + 8 * (i >> 2) + 4 * hh; }
; DI f32x16 zero16() { f32x16 z; for (int i = 0; i < 16; i++) z[i] = 0.f; return z; }
; #define DA_FETCH(T) { const int ktn_ = min((T), nkt - 1); \
;       _Pragma("unroll") for (int i = 0; i < 2; i++) rk[i] = *(const u32x4*)(Kbase + (size_t)(ktn_ * 64 + i * 32) * 64); \
;       _Pragma("unroll") for (int i = 0; i < 4; i++) rv[i] = *(const u32x4*)(Vbase + (size_t)ktn_ * 8192 + (size_t)(i * 32) * 64); }
; DI void da_item(const Params& P, int layer, int b, int h, int qt, char* mb, char* smem) {
;     ...
;     for (int kt = 0; kt < nkt; kt++) {
;       const u16* sK = sK0 + (kt & 1) * 64 * KS_;
;       const u16* sV = sV0 + (kt & 1) * 128 * VS_;
;       if (kt + 1 < nkt) { DA_STAGE((kt + 1) & 1) }
;       DA_FETCH(kt + 2)
;       if (kt * 64 <= qw + 31) {
;         f32x16 s[2];
; #pragma unroll
;         for (int kb = 0; kb < 2; kb++) {
;           s[kb] = zero16();
; #pragma unroll
;           for (int ks = 0; ks < 4; ks++) {
;             const bf16x8 kf = *(const bf16x8*)(sK + (kb * 32 + r) * KS_ + ks * 16 + hh * 8);
;             const bf16x8 qf = *(const bf16x8*)(sQw + r * KS_ + ks * 16 + hh * 8);
;             s[kb] = MFMA32(kf, qf, s[kb]);
;           }
;         }
;         const bool nearb = (kt * 64 + 63 + 128 > qw);
;         float mx = -INFINITY;
;         if (nearb) {
; #pragma unroll
;           for (int kb = 0; kb < 2; kb++)
; #pragma unroll
;             for (int i = 0; i < 16; i++) {
;               const int dist = qp - (kt * 64 + kb * 32 + crow(i, hh));
;               const float bv = sbias[min(max(dist, 0), 128)];
;               float t = s[kb][i] * SC + bv;
;               t = (dist >= 0) ? t : -INFINITY;
;               s[kb][i] = t; mx = fmaxf(mx, t);
;               if ((i & 7) == 7) __builtin_amdgcn_sched_barrier(0);
;             }
;         } else {
.LBB0_4120:
	s_add_i32 s4, s30, 2
	s_min_i32 s4, s4, s23
	s_lshl_b32 s44, s4, 6
	s_ashr_i32 s45, s44, 31
	s_lshl_b64 s[46:47], s[44:45], 7
	s_or_b32 s44, s44, 32
	s_ashr_i32 s45, s44, 31
	s_ashr_i32 s5, s4, 31
	v_lshl_add_u64 v[4:5], v[182:183], 0, s[46:47]
	s_lshl_b64 s[44:45], s[44:45], 7
	s_lshl_b64 s[4:5], s[4:5], 14
	v_lshl_add_u64 v[6:7], v[182:183], 0, s[44:45]
	global_load_dwordx4 v[114:117], v[4:5], off
	global_load_dwordx4 v[118:121], v[6:7], off
	v_lshl_add_u64 v[4:5], v[150:151], 0, s[4:5]
	v_add_co_u32_e32 v6, vcc, 0x1000, v4
	s_add_i32 s4, s10, 0xffffff41
	s_nop 0
	v_addc_co_u32_e32 v7, vcc, 0, v5, vcc
	global_load_dwordx4 v[122:125], v[4:5], off
	global_load_dwordx4 v[126:129], v[6:7], off
	v_add_co_u32_e32 v6, vcc, 0x2000, v4
	s_nop 1
	v_addc_co_u32_e32 v7, vcc, 0, v5, vcc
	v_add_co_u32_e32 v4, vcc, 0x3000, v4
	s_nop 1
	v_addc_co_u32_e32 v5, vcc, 0, v5, vcc
	global_load_dwordx4 v[130:133], v[6:7], off
	global_load_dwordx4 v[134:137], v[4:5], off
	v_cmp_le_i32_e32 vcc, s4, v214
	s_and_saveexec_b64 s[4:5], vcc
	s_cbranch_execz .LBB0_4128
	s_and_b32 s43, s30, 1
	s_mul_i32 s30, s43, 0x2400
	v_add_u32_e32 v3, s30, v215
	v_add_u32_e32 v16, v3, v211
	ds_read_b128 v[4:7], v16
	ds_read_b128 v[82:85], v16 offset:32
	v_add_u32_e32 v3, v3, v220
	v_cmp_le_i32_e32 vcc, s10, v210
	s_waitcnt lgkmcnt(1)
	v_mfma_f32_32x32x16_bf16 v[98:113], v[4:7], v[240:243], 0
	s_waitcnt lgkmcnt(0)
	v_mfma_f32_32x32x16_bf16 v[98:113], v[82:85], v[244:247], v[98:113]
	ds_read_b128 v[4:7], v16 offset:64
	ds_read_b128 v[82:85], v16 offset:96
	s_waitcnt lgkmcnt(1)
	v_mfma_f32_32x32x16_bf16 v[98:113], v[4:7], v[248:251], v[98:113]
	ds_read_b128 v[4:7], v3
	ds_read_b128 v[188:191], v3 offset:32
	s_waitcnt lgkmcnt(2)
	v_mfma_f32_32x32x16_bf16 v[98:113], v[82:85], v[252:255], v[98:113]
	s_waitcnt lgkmcnt(1)
	v_mfma_f32_32x32x16_bf16 v[82:97], v[4:7], v[240:243], 0
	ds_read_b128 v[4:7], v3 offset:64
	ds_read_b128 v[232:235], v3 offset:96
	s_waitcnt lgkmcnt(2)
	v_mfma_f32_32x32x16_bf16 v[82:97], v[188:191], v[244:247], v[82:97]
	s_waitcnt lgkmcnt(1)
	v_mfma_f32_32x32x16_bf16 v[82:97], v[4:7], v[248:251], v[82:97]
	s_waitcnt lgkmcnt(0)
	v_mfma_f32_32x32x16_bf16 v[82:97], v[232:235], v[252:255], v[82:97]
	s_and_saveexec_b64 s[30:31], vcc
	s_xor_b64 s[30:31], exec, s[30:31]
	s_cbranch_execz .LBB0_4123
	v_pk_fma_f32 v[4:5], v[98:99], s[20:21], v[138:139] op_sel_hi:[1,0,1]
	v_pk_fma_f32 v[6:7], v[100:101], s[20:21], v[138:139] op_sel_hi:[1,0,1]
	v_max3_f32 v3, v4, s36, v5
	v_max3_f32 v3, v3, v6, v7
	v_pk_fma_f32 v[8:9], v[102:103], s[20:21], v[138:139] op_sel_hi:[1,0,1]
	v_pk_fma_f32 v[10:11], v[104:105], s[20:21], v[138:139] op_sel_hi:[1,0,1]
	v_max3_f32 v3, v3, v8, v9
	v_max3_f32 v3, v3, v10, v11
	v_pk_fma_f32 v[12:13], v[106:107], s[20:21], v[138:139] op_sel_hi:[1,0,1]
	v_pk_fma_f32 v[14:15], v[108:109], s[20:21], v[138:139] op_sel_hi:[1,0,1]
	v_max3_f32 v3, v3, v12, v13
	v_max3_f32 v3, v3, v14, v15
	v_pk_fma_f32 v[16:17], v[110:111], s[20:21], v[138:139] op_sel_hi:[1,0,1]
	v_pk_fma_f32 v[184:185], v[112:113], s[20:21], v[138:139] op_sel_hi:[1,0,1]
	v_max3_f32 v3, v3, v16, v17
	v_max3_f32 v3, v3, v184, v185
	v_pk_fma_f32 v[186:187], v[82:83], s[20:21], v[138:139] op_sel_hi:[1,0,1]
	v_pk_fma_f32 v[188:189], v[84:85], s[20:21], v[138:139] op_sel_hi:[1,0,1]
	v_max3_f32 v3, v3, v186, v187
	v_max3_f32 v3, v3, v188, v189
	v_pk_fma_f32 v[190:191], v[86:87], s[20:21], v[138:139] op_sel_hi:[1,0,1]
	v_pk_fma_f32 v[192:193], v[88:89], s[20:21], v[138:139] op_sel_hi:[1,0,1]
	v_max3_f32 v3, v3, v190, v191
	v_max3_f32 v3, v3, v192, v193
	v_pk_fma_f32 v[200:201], v[90:91], s[20:21], v[138:139] op_sel_hi:[1,0,1]
	v_pk_fma_f32 v[198:199], v[92:93], s[20:21], v[138:139] op_sel_hi:[1,0,1]
	v_max3_f32 v3, v3, v200, v201
	v_max3_f32 v3, v3, v198, v199
	v_pk_fma_f32 v[196:197], v[94:95], s[20:21], v[138:139] op_sel_hi:[1,0,1]
	v_pk_fma_f32 v[194:195], v[96:97], s[20:21], v[138:139] op_sel_hi:[1,0,1]
	v_max3_f32 v3, v3, v196, v197
	v_max3_f32 v3, v3, v194, v195

; DI int tidx() { int t = threadIdx.x; asm volatile("" : "+v"(t)); return t; }
; #define GAS __attribute__((address_space(1)))
; DI void gemm_stage(const u16* __restrict__ A, int lda, const u16* __restrict__ B, int ldb, int kt, char* sbuf) {
;   const int tid = tidx(), lane = tid & 63, wave = __builtin_amdgcn_readfirstlane(tid >> 6);
;   const int pp = lane >> 4, pos = lane & 15;
; #pragma unroll
;   for (int i = 0; i < 4; i++) {
;     const int blk = i * 4 + wave;
;     const int p = blk * 4 + pp;
;     const int row = 2 * p + (pos >> 3), c8 = (pos & 7) ^ (p & 7);
;     const u16* ga = A + (size_t)row * lda + kt * 64 + c8 * 8;
;     const u16* gb = B + (size_t)row * ldb + kt * 64 + c8 * 8;
;     __builtin_amdgcn_global_load_lds((const GAS void*)ga, (__attribute__((address_space(3))) void*)(sbuf + blk * 1024), 16, 0, 0);
;     __builtin_amdgcn_global_load_lds((const GAS void*)gb, (__attribute__((address_space(3))) void*)(sbuf + 16384 + blk * 1024), 16, 0, 0);
;   }
.LBB0_4314:
	s_setprio 1
	s_mov_b32 s15, 0
	s_mov_b32 s30, 0
	v_readfirstlane_b32 s31, v202
	v_bfe_u32 v238, v202, 4, 2
	v_bfe_u32 v239, v202, 3, 1
	s_ashr_i32 s31, s31, 6
	s_lshl_b32 s17, s31, 3
	v_lshlrev_b32_e32 v90, 1, v238
	v_or3_b32 v90, s17, v90, v239
	v_lshl_or_b32 v238, s31, 2, v238
	v_bitop3_b32 v238, v238, 7, v202 bitop3:0x48
	v_lshlrev_b32_e32 v238, 4, v238
	v_mul_u32_u24_e32 v90, 0x200, v90
	v_add_u32_e32 v238, v90, v238
	v_add_u32_e32 v239, 0x4000, v238
	s_lshl_b32 s31, s31, 10
	s_add_u32 s12, s8, 0x8000
	s_addc_u32 s13, s9, 0
	s_add_u32 s18, s10, 0x8000
	s_addc_u32 s19, s11, 0

; #define MFMA32(a, b, c) __builtin_amdgcn_mfma_f32_32x32x16_bf16((a), (b), (c), 0, 0, 0)
; DI void gemm_main(f32x16 (&acc)[2][2], const u16* __restrict__ A, int lda, const u16* __restrict__ B, int ldb, int K, u16* sm) {
;     ...
;     for (int ks = 0; ks < 4; ks++) {
;       const int ca = ((ks * 2 + hh) ^ xa) << 4, cb = ((ks * 2 + hh) ^ xb) << 4;
;       const bf16x8 fa0 = *(const bf16x8*)(st + baseA + ca);
;       const bf16x8 fa1 = *(const bf16x8*)(st + baseA + 4096 + ca);
;       const bf16x8 fb0 = *(const bf16x8*)(st + baseB + cb);
;       const bf16x8 fb1 = *(const bf16x8*)(st + baseB + 4096 + cb);
;       acc[0][0] = MFMA32(fa0, fb0, acc[0][0]); acc[0][1] = MFMA32(fa0, fb1, acc[0][1]);
;       acc[1][0] = MFMA32(fa1, fb0, acc[1][0]); acc[1][1] = MFMA32(fa1, fb1, acc[1][1]);
;     }
;     asm volatile("s_waitcnt vmcnt(0)" ::: "memory");
;     __syncthreads();
.Lkl2_last:
	v_add_u32_e32 v90, s15, v68
	v_add3_u32 v91, s15, v69, v66
	v_add_u32_e32 v82, v90, v70
	v_add_u32_e32 v86, v91, v70
	ds_read_b128 v[74:77], v82
	ds_read_b128 v[78:81], v86 offset:16384
	ds_read_b128 v[82:85], v82 offset:4096
	ds_read_b128 v[86:89], v86 offset:20480
	v_add_u32_e32 v248, v90, v71
	v_add_u32_e32 v252, v91, v71
	ds_read_b128 v[240:243], v248
	ds_read_b128 v[244:247], v252 offset:16384
	ds_read_b128 v[248:251], v248 offset:4096
	ds_read_b128 v[252:255], v252 offset:20480
	s_waitcnt lgkmcnt(4)
	v_mfma_f32_32x32x16_bf16 v[18:33], v[82:85], v[78:81], v[18:33]
	v_mfma_f32_32x32x16_bf16 v[2:17], v[82:85], v[86:89], v[2:17]
	v_mfma_f32_32x32x16_bf16 v[50:65], v[74:77], v[78:81], v[50:65]
	v_mfma_f32_32x32x16_bf16 v[34:49], v[74:77], v[86:89], v[34:49]
	v_add_u32_e32 v82, v90, v72
	v_add_u32_e32 v86, v91, v72
	ds_read_b128 v[74:77], v82
	ds_read_b128 v[78:81], v86 offset:16384
	ds_read_b128 v[82:85], v82 offset:4096
	ds_read_b128 v[86:89], v86 offset:20480
	s_waitcnt lgkmcnt(4)
	v_mfma_f32_32x32x16_bf16 v[18:33], v[248:251], v[244:247], v[18:33]
	v_mfma_f32_32x32x16_bf16 v[2:17], v[248:251], v[252:255], v[2:17]
	v_mfma_f32_32x32x16_bf16 v[50:65], v[240:243], v[244:247], v[50:65]
	v_mfma_f32_32x32x16_bf16 v[34:49], v[240:243], v[252:255], v[34:49]
	v_add_u32_e32 v248, v90, v73
	v_add_u32_e32 v252, v91, v73
	ds_read_b128 v[240:243], v248
	ds_read_b128 v[244:247], v252 offset:16384
	ds_read_b128 v[248:251], v248 offset:4096
	ds_read_b128 v[252:255], v252 offset:20480
	s_waitcnt lgkmcnt(4)
	v_mfma_f32_32x32x16_bf16 v[18:33], v[82:85], v[78:81], v[18:33]
	v_mfma_f32_32x32x16_bf16 v[2:17], v[82:85], v[86:89], v[2:17]
	v_mfma_f32_32x32x16_bf16 v[50:65], v[74:77], v[78:81], v[50:65]
	v_mfma_f32_32x32x16_bf16 v[34:49], v[74:77], v[86:89], v[34:49]
	s_add_i32 s30, s30, 1
	s_waitcnt vmcnt(0) lgkmcnt(0)
	s_barrier
	v_mfma_f32_32x32x16_bf16 v[50:65], v[240:243], v[244:247], v[50:65]
	v_mfma_f32_32x32x16_bf16 v[34:49], v[240:243], v[252:255], v[34:49]
	v_mfma_f32_32x32x16_bf16 v[18:33], v[248:251], v[244:247], v[18:33]
	v_mfma_f32_32x32x16_bf16 v[2:17], v[248:251], v[252:255], v[2:17]
	s_setprio 0
	s_branch .LBB0_4318

; DI int tidx() { int t = threadIdx.x; asm volatile("" : "+v"(t)); return t; }
; #define GAS __attribute__((address_space(1)))
; DI void gemm_stage(const u16* __restrict__ A, int lda, const u16* __restrict__ B, int ldb, int kt, char* sbuf) {
;   const int tid = tidx(), lane = tid & 63, wave = __builtin_amdgcn_readfirstlane(tid >> 6);
;   const int pp = lane >> 4, pos = lane & 15;
; #pragma unroll
;   for (int i = 0; i < 4; i++) {
;     const int blk = i * 4 + wave;
;     const int p = blk * 4 + pp;
;     const int row = 2 * p + (pos >> 3), c8 = (pos & 7) ^ (p & 7);
;     const u16* ga = A + (size_t)row * lda + kt * 64 + c8 * 8;
;     const u16* gb = B + (size_t)row * ldb + kt * 64 + c8 * 8;
;     __builtin_amdgcn_global_load_lds((const GAS void*)ga, (__attribute__((address_space(3))) void*)(sbuf + blk * 1024), 16, 0, 0);
;     __builtin_amdgcn_global_load_lds((const GAS void*)gb, (__attribute__((address_space(3))) void*)(sbuf + 16384 + blk * 1024), 16, 0, 0);
;   }
.LBB0_4410:
	s_setprio 1
	s_mov_b32 s29, 0
	s_mov_b32 s31, 0
	v_readfirstlane_b32 s33, v202
	v_bfe_u32 v238, v202, 4, 2
	v_bfe_u32 v239, v202, 3, 1
	s_ashr_i32 s33, s33, 6
	s_lshl_b32 s30, s33, 3
	v_lshlrev_b32_e32 v173, 1, v238
	v_or3_b32 v173, s30, v173, v239
	v_lshl_or_b32 v238, s33, 2, v238
	v_bitop3_b32 v238, v238, 7, v202 bitop3:0x48
	v_lshlrev_b32_e32 v238, 4, v238
	v_mul_u32_u24_e32 v173, 0x800, v173
	v_add_u32_e32 v238, v173, v238
	v_add_u32_e32 v239, 0x10000, v238
	s_lshl_b32 s33, s33, 10
	s_add_u32 s14, s10, 0x20000
	s_addc_u32 s15, s11, 0
	s_add_u32 s16, s12, 0x20000
	s_addc_u32 s17, s13, 0

; #define MFMA32(a, b, c) __builtin_amdgcn_mfma_f32_32x32x16_bf16((a), (b), (c), 0, 0, 0)
; DI void gemm_main(f32x16 (&acc)[2][2], const u16* __restrict__ A, int lda, const u16* __restrict__ B, int ldb, int K, u16* sm) {
;     ...
;     for (int ks = 0; ks < 4; ks++) {
;       const int ca = ((ks * 2 + hh) ^ xa) << 4, cb = ((ks * 2 + hh) ^ xb) << 4;
;       const bf16x8 fa0 = *(const bf16x8*)(st + baseA + ca);
;       const bf16x8 fa1 = *(const bf16x8*)(st + baseA + 4096 + ca);
;       const bf16x8 fb0 = *(const bf16x8*)(st + baseB + cb);
;       const bf16x8 fb1 = *(const bf16x8*)(st + baseB + 4096 + cb);
;       acc[0][0] = MFMA32(fa0, fb0, acc[0][0]); acc[0][1] = MFMA32(fa0, fb1, acc[0][1]);
;       acc[1][0] = MFMA32(fa1, fb0, acc[1][0]); acc[1][1] = MFMA32(fa1, fb1, acc[1][1]);
;     }
;     asm volatile("s_waitcnt vmcnt(0)" ::: "memory");
;     __syncthreads();
.Lkl3_last:
	v_add_u32_e32 v173, s29, v167
	v_add3_u32 v190, s29, v168, v71
	v_add_u32_e32 v182, v173, v169
	v_add_u32_e32 v186, v190, v169
	ds_read_b128 v[174:177], v182
	ds_read_b128 v[178:181], v186 offset:16384
	ds_read_b128 v[182:185], v182 offset:4096
	ds_read_b128 v[186:189], v186 offset:20480
	v_add_u32_e32 v248, v173, v170
	v_add_u32_e32 v252, v190, v170
	ds_read_b128 v[240:243], v248
	ds_read_b128 v[244:247], v252 offset:16384
	ds_read_b128 v[248:251], v248 offset:4096
	ds_read_b128 v[252:255], v252 offset:20480
	s_waitcnt lgkmcnt(4)
	v_mfma_f32_32x32x16_bf16 v[18:33], v[182:185], v[178:181], v[18:33]
	v_mfma_f32_32x32x16_bf16 v[34:49], v[182:185], v[186:189], v[34:49]
	v_mfma_f32_32x32x16_bf16 v[2:17], v[174:177], v[178:181], v[2:17]
	v_mfma_f32_32x32x16_bf16 v[50:65], v[174:177], v[186:189], v[50:65]
	v_add_u32_e32 v182, v173, v171
	v_add_u32_e32 v186, v190, v171
	ds_read_b128 v[174:177], v182
	ds_read_b128 v[178:181], v186 offset:16384
	ds_read_b128 v[182:185], v182 offset:4096
	ds_read_b128 v[186:189], v186 offset:20480
	s_waitcnt lgkmcnt(4)
	v_mfma_f32_32x32x16_bf16 v[18:33], v[248:251], v[244:247], v[18:33]
	v_mfma_f32_32x32x16_bf16 v[34:49], v[248:251], v[252:255], v[34:49]
	v_mfma_f32_32x32x16_bf16 v[2:17], v[240:243], v[244:247], v[2:17]
	v_mfma_f32_32x32x16_bf16 v[50:65], v[240:243], v[252:255], v[50:65]
	v_add_u32_e32 v248, v173, v172
	v_add_u32_e32 v252, v190, v172
	ds_read_b128 v[240:243], v248
	ds_read_b128 v[244:247], v252 offset:16384
	ds_read_b128 v[248:251], v248 offset:4096
	ds_read_b128 v[252:255], v252 offset:20480
	s_waitcnt lgkmcnt(4)
	v_mfma_f32_32x32x16_bf16 v[18:33], v[182:185], v[178:181], v[18:33]
	v_mfma_f32_32x32x16_bf16 v[34:49], v[182:185], v[186:189], v[34:49]
	v_mfma_f32_32x32x16_bf16 v[2:17], v[174:177], v[178:181], v[2:17]
	v_mfma_f32_32x32x16_bf16 v[50:65], v[174:177], v[186:189], v[50:65]
	s_add_i32 s31, s31, 1
	s_waitcnt vmcnt(0) lgkmcnt(0)
	s_barrier
	v_mfma_f32_32x32x16_bf16 v[2:17], v[240:243], v[244:247], v[2:17]
	v_mfma_f32_32x32x16_bf16 v[50:65], v[240:243], v[252:255], v[50:65]
	v_mfma_f32_32x32x16_bf16 v[18:33], v[248:251], v[244:247], v[18:33]
	v_mfma_f32_32x32x16_bf16 v[34:49], v[248:251], v[252:255], v[34:49]
	s_setprio 0
	s_branch .LBB0_4414

; DI int tidx() { int t = threadIdx.x; asm volatile("" : "+v"(t)); return t; }
; #define GAS __attribute__((address_space(1)))
; DI void gemm_stage(const u16* __restrict__ A, int lda, const u16* __restrict__ B, int ldb, int kt, char* sbuf) {
;   const int tid = tidx(), lane = tid & 63, wave = __builtin_amdgcn_readfirstlane(tid >> 6);
;   const int pp = lane >> 4, pos = lane & 15;
; #pragma unroll
;   for (int i = 0; i < 4; i++) {
;     const int blk = i * 4 + wave;
;     const int p = blk * 4 + pp;
;     const int row = 2 * p + (pos >> 3), c8 = (pos & 7) ^ (p & 7);
;     const u16* ga = A + (size_t)row * lda + kt * 64 + c8 * 8;
;     const u16* gb = B + (size_t)row * ldb + kt * 64 + c8 * 8;
;     __builtin_amdgcn_global_load_lds((const GAS void*)ga, (__attribute__((address_space(3))) void*)(sbuf + blk * 1024), 16, 0, 0);
;     __builtin_amdgcn_global_load_lds((const GAS void*)gb, (__attribute__((address_space(3))) void*)(sbuf + 16384 + blk * 1024), 16, 0, 0);
;   }
.LBB0_4578:
	s_setprio 1
	s_mov_b32 s13, 0
	s_mov_b32 s36, 0
	v_readfirstlane_b32 s37, v202
	v_bfe_u32 v238, v202, 4, 2
	v_bfe_u32 v239, v202, 3, 1
	s_ashr_i32 s37, s37, 6
	s_lshl_b32 s15, s37, 3
	v_lshlrev_b32_e32 v122, 1, v238
	v_or3_b32 v122, s15, v122, v239
	v_lshl_or_b32 v238, s37, 2, v238
	v_bitop3_b32 v238, v238, 7, v202 bitop3:0x48
	v_lshlrev_b32_e32 v238, 4, v238
	v_mul_u32_u24_e32 v122, 0x800, v122
	v_add_u32_e32 v238, v122, v238
	v_add_u32_e32 v239, 0x10000, v238
	s_lshl_b32 s37, s37, 10
	s_add_u32 s16, s8, 0x20000
	s_addc_u32 s17, s9, 0
	s_add_u32 s18, s10, 0x20000
	s_addc_u32 s19, s11, 0

; #define MFMA32(a, b, c) __builtin_amdgcn_mfma_f32_32x32x16_bf16((a), (b), (c), 0, 0, 0)
; DI void gemm_main(f32x16 (&acc)[2][2], const u16* __restrict__ A, int lda, const u16* __restrict__ B, int ldb, int K, u16* sm) {
;     ...
;     for (int ks = 0; ks < 4; ks++) {
;       const int ca = ((ks * 2 + hh) ^ xa) << 4, cb = ((ks * 2 + hh) ^ xb) << 4;
;       const bf16x8 fa0 = *(const bf16x8*)(st + baseA + ca);
;       const bf16x8 fa1 = *(const bf16x8*)(st + baseA + 4096 + ca);
;       const bf16x8 fb0 = *(const bf16x8*)(st + baseB + cb);
;       const bf16x8 fb1 = *(const bf16x8*)(st + baseB + 4096 + cb);
;       acc[0][0] = MFMA32(fa0, fb0, acc[0][0]); acc[0][1] = MFMA32(fa0, fb1, acc[0][1]);
;       acc[1][0] = MFMA32(fa1, fb0, acc[1][0]); acc[1][1] = MFMA32(fa1, fb1, acc[1][1]);
;     }
;     asm volatile("s_waitcnt vmcnt(0)" ::: "memory");
;     __syncthreads();
.Lkl4_last:
	v_add_u32_e32 v122, s13, v68
	v_add3_u32 v123, s13, v69, v66
	v_add_u32_e32 v114, v122, v102
	v_add_u32_e32 v118, v123, v102
	ds_read_b128 v[106:109], v114
	ds_read_b128 v[110:113], v118 offset:16384
	ds_read_b128 v[114:117], v114 offset:4096
	ds_read_b128 v[118:121], v118 offset:20480
	v_add_u32_e32 v248, v122, v103
	v_add_u32_e32 v252, v123, v103
	ds_read_b128 v[240:243], v248
	ds_read_b128 v[244:247], v252 offset:16384
	ds_read_b128 v[248:251], v248 offset:4096
	ds_read_b128 v[252:255], v252 offset:20480
	s_waitcnt lgkmcnt(4)
	v_mfma_f32_32x32x16_bf16 v[18:33], v[114:117], v[110:113], v[18:33]
	v_mfma_f32_32x32x16_bf16 v[2:17], v[114:117], v[118:121], v[2:17]
	v_mfma_f32_32x32x16_bf16 v[50:65], v[106:109], v[110:113], v[50:65]
	v_mfma_f32_32x32x16_bf16 v[34:49], v[106:109], v[118:121], v[34:49]
	v_add_u32_e32 v114, v122, v104
	v_add_u32_e32 v118, v123, v104
	ds_read_b128 v[106:109], v114
	ds_read_b128 v[110:113], v118 offset:16384
	ds_read_b128 v[114:117], v114 offset:4096
	ds_read_b128 v[118:121], v118 offset:20480
	s_waitcnt lgkmcnt(4)
	v_mfma_f32_32x32x16_bf16 v[18:33], v[248:251], v[244:247], v[18:33]
	v_mfma_f32_32x32x16_bf16 v[2:17], v[248:251], v[252:255], v[2:17]
	v_mfma_f32_32x32x16_bf16 v[50:65], v[240:243], v[244:247], v[50:65]
	v_mfma_f32_32x32x16_bf16 v[34:49], v[240:243], v[252:255], v[34:49]
	v_add_u32_e32 v248, v122, v105
	v_add_u32_e32 v252, v123, v105
	ds_read_b128 v[240:243], v248
	ds_read_b128 v[244:247], v252 offset:16384
	ds_read_b128 v[248:251], v248 offset:4096
	ds_read_b128 v[252:255], v252 offset:20480
	s_waitcnt lgkmcnt(4)
	v_mfma_f32_32x32x16_bf16 v[18:33], v[114:117], v[110:113], v[18:33]
	v_mfma_f32_32x32x16_bf16 v[2:17], v[114:117], v[118:121], v[2:17]
	v_mfma_f32_32x32x16_bf16 v[50:65], v[106:109], v[110:113], v[50:65]
	v_mfma_f32_32x32x16_bf16 v[34:49], v[106:109], v[118:121], v[34:49]
	s_add_i32 s36, s36, 1
	s_waitcnt vmcnt(0) lgkmcnt(0)
	s_barrier
	v_mfma_f32_32x32x16_bf16 v[50:65], v[240:243], v[244:247], v[50:65]
	v_mfma_f32_32x32x16_bf16 v[34:49], v[240:243], v[252:255], v[34:49]
	v_mfma_f32_32x32x16_bf16 v[18:33], v[248:251], v[244:247], v[18:33]
	v_mfma_f32_32x32x16_bf16 v[2:17], v[248:251], v[252:255], v[2:17]
	s_setprio 0
	s_branch .LBB0_4582

; DI int tidx() { int t = threadIdx.x; asm volatile("" : "+v"(t)); return t; }
; #define GAS __attribute__((address_space(1)))
; DI void gemm_stage(const u16* __restrict__ A, int lda, const u16* __restrict__ B, int ldb, int kt, char* sbuf) {
;   const int tid = tidx(), lane = tid & 63, wave = __builtin_amdgcn_readfirstlane(tid >> 6);
;   const int pp = lane >> 4, pos = lane & 15;
; #pragma unroll
;   for (int i = 0; i < 4; i++) {
;     const int blk = i * 4 + wave;
;     const int p = blk * 4 + pp;
;     const int row = 2 * p + (pos >> 3), c8 = (pos & 7) ^ (p & 7);
;     const u16* ga = A + (size_t)row * lda + kt * 64 + c8 * 8;
;     const u16* gb = B + (size_t)row * ldb + kt * 64 + c8 * 8;
;     __builtin_amdgcn_global_load_lds((const GAS void*)ga, (__attribute__((address_space(3))) void*)(sbuf + blk * 1024), 16, 0, 0);
;     __builtin_amdgcn_global_load_lds((const GAS void*)gb, (__attribute__((address_space(3))) void*)(sbuf + 16384 + blk * 1024), 16, 0, 0);
;   }
.LBB0_4605:
	s_setprio 1
	s_mov_b32 s15, 0
	s_mov_b32 s35, 0
	v_readfirstlane_b32 s36, v202
	v_bfe_u32 v238, v202, 4, 2
	v_bfe_u32 v239, v202, 3, 1
	s_ashr_i32 s36, s36, 6
	s_lshl_b32 s17, s36, 3
	v_lshlrev_b32_e32 v111, 1, v238
	v_or3_b32 v111, s17, v111, v239
	v_lshl_or_b32 v238, s36, 2, v238
	v_bitop3_b32 v238, v238, 7, v202 bitop3:0x48
	v_lshlrev_b32_e32 v238, 4, v238
	v_mul_u32_u24_e32 v111, 0x800, v111
	v_add_u32_e32 v238, v111, v238
	v_add_u32_e32 v239, 0x10000, v238
	s_lshl_b32 s36, s36, 10
	s_add_u32 s12, s8, 0x20000
	s_addc_u32 s13, s9, 0
	s_add_u32 s18, s10, 0x20000
	s_addc_u32 s19, s11, 0

; #define MFMA32(a, b, c) __builtin_amdgcn_mfma_f32_32x32x16_bf16((a), (b), (c), 0, 0, 0)
; DI void gemm_main(f32x16 (&acc)[2][2], const u16* __restrict__ A, int lda, const u16* __restrict__ B, int ldb, int K, u16* sm) {
;     ...
;     for (int ks = 0; ks < 4; ks++) {
;       const int ca = ((ks * 2 + hh) ^ xa) << 4, cb = ((ks * 2 + hh) ^ xb) << 4;
;       const bf16x8 fa0 = *(const bf16x8*)(st + baseA + ca);
;       const bf16x8 fa1 = *(const bf16x8*)(st + baseA + 4096 + ca);
;       const bf16x8 fb0 = *(const bf16x8*)(st + baseB + cb);
;       const bf16x8 fb1 = *(const bf16x8*)(st + baseB + 4096 + cb);
;       acc[0][0] = MFMA32(fa0, fb0, acc[0][0]); acc[0][1] = MFMA32(fa0, fb1, acc[0][1]);
;       acc[1][0] = MFMA32(fa1, fb0, acc[1][0]); acc[1][1] = MFMA32(fa1, fb1, acc[1][1]);
;     }
;     asm volatile("s_waitcnt vmcnt(0)" ::: "memory");
;     __syncthreads();
.Lkl5_last:
	v_add_u32_e32 v111, s15, v74
	v_add3_u32 v128, s15, v75, v70
	v_add_u32_e32 v120, v111, v76
	v_add_u32_e32 v124, v128, v76
	ds_read_b128 v[112:115], v120
	ds_read_b128 v[116:119], v124 offset:16384
	ds_read_b128 v[120:123], v120 offset:4096
	ds_read_b128 v[124:127], v124 offset:20480
	v_add_u32_e32 v248, v111, v77
	v_add_u32_e32 v252, v128, v77
	ds_read_b128 v[240:243], v248
	ds_read_b128 v[244:247], v252 offset:16384
	ds_read_b128 v[248:251], v248 offset:4096
	ds_read_b128 v[252:255], v252 offset:20480
	s_waitcnt lgkmcnt(4)
	v_mfma_f32_32x32x16_bf16 v[18:33], v[120:123], v[116:119], v[18:33]
	v_mfma_f32_32x32x16_bf16 v[2:17], v[120:123], v[124:127], v[2:17]
	v_mfma_f32_32x32x16_bf16 v[50:65], v[112:115], v[116:119], v[50:65]
	v_mfma_f32_32x32x16_bf16 v[34:49], v[112:115], v[124:127], v[34:49]
	v_add_u32_e32 v120, v111, v109
	v_add_u32_e32 v124, v128, v109
	ds_read_b128 v[112:115], v120
	ds_read_b128 v[116:119], v124 offset:16384
	ds_read_b128 v[120:123], v120 offset:4096
	ds_read_b128 v[124:127], v124 offset:20480
	s_waitcnt lgkmcnt(4)
	v_mfma_f32_32x32x16_bf16 v[18:33], v[248:251], v[244:247], v[18:33]
	v_mfma_f32_32x32x16_bf16 v[2:17], v[248:251], v[252:255], v[2:17]
	v_mfma_f32_32x32x16_bf16 v[50:65], v[240:243], v[244:247], v[50:65]
	v_mfma_f32_32x32x16_bf16 v[34:49], v[240:243], v[252:255], v[34:49]
	v_add_u32_e32 v248, v111, v110
	v_add_u32_e32 v252, v128, v110
	ds_read_b128 v[240:243], v248
	ds_read_b128 v[244:247], v252 offset:16384
	ds_read_b128 v[248:251], v248 offset:4096
	ds_read_b128 v[252:255], v252 offset:20480
	s_waitcnt lgkmcnt(4)
	v_mfma_f32_32x32x16_bf16 v[18:33], v[120:123], v[116:119], v[18:33]
	v_mfma_f32_32x32x16_bf16 v[2:17], v[120:123], v[124:127], v[2:17]
	v_mfma_f32_32x32x16_bf16 v[50:65], v[112:115], v[116:119], v[50:65]
	v_mfma_f32_32x32x16_bf16 v[34:49], v[112:115], v[124:127], v[34:49]
	s_add_i32 s35, s35, 1
	s_waitcnt vmcnt(0) lgkmcnt(0)
	s_barrier
	v_mfma_f32_32x32x16_bf16 v[50:65], v[240:243], v[244:247], v[50:65]
	v_mfma_f32_32x32x16_bf16 v[34:49], v[240:243], v[252:255], v[34:49]
	v_mfma_f32_32x32x16_bf16 v[18:33], v[248:251], v[244:247], v[18:33]
	v_mfma_f32_32x32x16_bf16 v[2:17], v[248:251], v[252:255], v[2:17]
	s_setprio 0
	s_branch .LBB0_4609

; DI int tidx() { int t = threadIdx.x; asm volatile("" : "+v"(t)); return t; }
; #define GAS __attribute__((address_space(1)))
; DI void gemm_stage(const u16* __restrict__ A, int lda, const u16* __restrict__ B, int ldb, int kt, char* sbuf) {
;   const int tid = tidx(), lane = tid & 63, wave = __builtin_amdgcn_readfirstlane(tid >> 6);
;   const int pp = lane >> 4, pos = lane & 15;
; #pragma unroll
;   for (int i = 0; i < 4; i++) {
;     const int blk = i * 4 + wave;
;     const int p = blk * 4 + pp;
;     const int row = 2 * p + (pos >> 3), c8 = (pos & 7) ^ (p & 7);
;     const u16* ga = A + (size_t)row * lda + kt * 64 + c8 * 8;
;     const u16* gb = B + (size_t)row * ldb + kt * 64 + c8 * 8;
;     __builtin_amdgcn_global_load_lds((const GAS void*)ga, (__attribute__((address_space(3))) void*)(sbuf + blk * 1024), 16, 0, 0);
;     __builtin_amdgcn_global_load_lds((const GAS void*)gb, (__attribute__((address_space(3))) void*)(sbuf + 16384 + blk * 1024), 16, 0, 0);
;   }
.LBB0_4632:
	s_setprio 1
	s_mov_b32 s7, 0
	s_mov_b32 s28, 0
	v_readfirstlane_b32 s29, v202
	v_bfe_u32 v238, v202, 4, 2
	v_bfe_u32 v239, v202, 3, 1
	s_ashr_i32 s29, s29, 6
	s_lshl_b32 s13, s29, 3
	v_lshlrev_b32_e32 v92, 1, v238
	v_or3_b32 v92, s13, v92, v239
	v_lshl_or_b32 v238, s29, 2, v238
	v_bitop3_b32 v238, v238, 7, v202 bitop3:0x48
	v_lshlrev_b32_e32 v238, 4, v238
	v_mul_u32_u24_e32 v92, 0x200, v92
	v_add_u32_e32 v238, v92, v238
	v_add_u32_e32 v239, 0x4000, v238
	s_lshl_b32 s29, s29, 10
	s_add_u32 s10, s4, 0x8000
	s_addc_u32 s11, s5, 0
	s_add_u32 s14, s8, 0x8000
	s_addc_u32 s15, s9, 0

; #define MFMA32(a, b, c) __builtin_amdgcn_mfma_f32_32x32x16_bf16((a), (b), (c), 0, 0, 0)
; DI void gemm_main(f32x16 (&acc)[2][2], const u16* __restrict__ A, int lda, const u16* __restrict__ B, int ldb, int K, u16* sm) {
;     ...
;     for (int ks = 0; ks < 4; ks++) {
;       const int ca = ((ks * 2 + hh) ^ xa) << 4, cb = ((ks * 2 + hh) ^ xb) << 4;
;       const bf16x8 fa0 = *(const bf16x8*)(st + baseA + ca);
;       const bf16x8 fa1 = *(const bf16x8*)(st + baseA + 4096 + ca);
;       const bf16x8 fb0 = *(const bf16x8*)(st + baseB + cb);
;       const bf16x8 fb1 = *(const bf16x8*)(st + baseB + 4096 + cb);
;       acc[0][0] = MFMA32(fa0, fb0, acc[0][0]); acc[0][1] = MFMA32(fa0, fb1, acc[0][1]);
;       acc[1][0] = MFMA32(fa1, fb0, acc[1][0]); acc[1][1] = MFMA32(fa1, fb1, acc[1][1]);
;     }
;     asm volatile("s_waitcnt vmcnt(0)" ::: "memory");
;     __syncthreads();
.Lkl6_last:
	v_add_u32_e32 v92, s7, v69
	v_add3_u32 v93, s7, v70, v68
	v_add_u32_e32 v84, v92, v72
	v_add_u32_e32 v88, v93, v72
	ds_read_b128 v[76:79], v84
	ds_read_b128 v[80:83], v88 offset:16384
	ds_read_b128 v[84:87], v84 offset:4096
	ds_read_b128 v[88:91], v88 offset:20480
	v_add_u32_e32 v248, v92, v73
	v_add_u32_e32 v252, v93, v73
	ds_read_b128 v[240:243], v248
	ds_read_b128 v[244:247], v252 offset:16384
	ds_read_b128 v[248:251], v248 offset:4096
	ds_read_b128 v[252:255], v252 offset:20480
	s_waitcnt lgkmcnt(4)
	v_mfma_f32_32x32x16_bf16 v[18:33], v[84:87], v[80:83], v[18:33]
	v_mfma_f32_32x32x16_bf16 v[2:17], v[84:87], v[88:91], v[2:17]
	v_mfma_f32_32x32x16_bf16 v[50:65], v[76:79], v[80:83], v[50:65]
	v_mfma_f32_32x32x16_bf16 v[34:49], v[76:79], v[88:91], v[34:49]
	v_add_u32_e32 v84, v92, v74
	v_add_u32_e32 v88, v93, v74
	ds_read_b128 v[76:79], v84
	ds_read_b128 v[80:83], v88 offset:16384
	ds_read_b128 v[84:87], v84 offset:4096
	ds_read_b128 v[88:91], v88 offset:20480
	s_waitcnt lgkmcnt(4)
	v_mfma_f32_32x32x16_bf16 v[18:33], v[248:251], v[244:247], v[18:33]
	v_mfma_f32_32x32x16_bf16 v[2:17], v[248:251], v[252:255], v[2:17]
	v_mfma_f32_32x32x16_bf16 v[50:65], v[240:243], v[244:247], v[50:65]
	v_mfma_f32_32x32x16_bf16 v[34:49], v[240:243], v[252:255], v[34:49]
	v_add_u32_e32 v248, v92, v75
	v_add_u32_e32 v252, v93, v75
	ds_read_b128 v[240:243], v248
	ds_read_b128 v[244:247], v252 offset:16384
	ds_read_b128 v[248:251], v248 offset:4096
	ds_read_b128 v[252:255], v252 offset:20480
	s_waitcnt lgkmcnt(4)
	v_mfma_f32_32x32x16_bf16 v[18:33], v[84:87], v[80:83], v[18:33]
	v_mfma_f32_32x32x16_bf16 v[2:17], v[84:87], v[88:91], v[2:17]
	v_mfma_f32_32x32x16_bf16 v[50:65], v[76:79], v[80:83], v[50:65]
	v_mfma_f32_32x32x16_bf16 v[34:49], v[76:79], v[88:91], v[34:49]
	s_add_i32 s28, s28, 1
	s_waitcnt vmcnt(0) lgkmcnt(0)
	s_barrier
	v_mfma_f32_32x32x16_bf16 v[50:65], v[240:243], v[244:247], v[50:65]
	v_mfma_f32_32x32x16_bf16 v[34:49], v[240:243], v[252:255], v[34:49]
	v_mfma_f32_32x32x16_bf16 v[18:33], v[248:251], v[244:247], v[18:33]
	v_mfma_f32_32x32x16_bf16 v[2:17], v[248:251], v[252:255], v[2:17]
	s_setprio 0
	s_branch .LBB0_4636

; DI int tidx() { int t = threadIdx.x; asm volatile("" : "+v"(t)); return t; }
; #define GAS __attribute__((address_space(1)))
; DI void gemm_stage(const u16* __restrict__ A, int lda, const u16* __restrict__ B, int ldb, int kt, char* sbuf) {
;   const int tid = tidx(), lane = tid & 63, wave = __builtin_amdgcn_readfirstlane(tid >> 6);
;   const int pp = lane >> 4, pos = lane & 15;
; #pragma unroll
;   for (int i = 0; i < 4; i++) {
;     const int blk = i * 4 + wave;
;     const int p = blk * 4 + pp;
;     const int row = 2 * p + (pos >> 3), c8 = (pos & 7) ^ (p & 7);
;     const u16* ga = A + (size_t)row * lda + kt * 64 + c8 * 8;
;     const u16* gb = B + (size_t)row * ldb + kt * 64 + c8 * 8;
;     __builtin_amdgcn_global_load_lds((const GAS void*)ga, (__attribute__((address_space(3))) void*)(sbuf + blk * 1024), 16, 0, 0);
;     __builtin_amdgcn_global_load_lds((const GAS void*)gb, (__attribute__((address_space(3))) void*)(sbuf + 16384 + blk * 1024), 16, 0, 0);
;   }
.LBB0_4728:
	s_setprio 1
	s_mov_b32 s36, 0
	s_mov_b32 s38, 0
	v_readfirstlane_b32 s39, v202
	v_bfe_u32 v238, v202, 4, 2
	v_bfe_u32 v239, v202, 3, 1
	s_ashr_i32 s39, s39, 6
	s_lshl_b32 s37, s39, 3
	v_lshlrev_b32_e32 v188, 1, v238
	v_or3_b32 v188, s37, v188, v239
	v_lshl_or_b32 v238, s39, 2, v238
	v_bitop3_b32 v238, v238, 7, v202 bitop3:0x48
	v_lshlrev_b32_e32 v238, 4, v238
	v_mul_u32_u24_e32 v188, 0x1600, v188
	v_add_u32_e32 v238, v188, v238
	v_add_u32_e32 v239, 0x2c000, v238
	s_lshl_b32 s39, s39, 10
	s_add_u32 s18, s14, 0x58000
	s_addc_u32 s19, s15, 0
	s_add_u32 s20, s16, 0x58000
	s_addc_u32 s21, s17, 0

; #define MFMA32(a, b, c) __builtin_amdgcn_mfma_f32_32x32x16_bf16((a), (b), (c), 0, 0, 0)
; DI void gemm_main(f32x16 (&acc)[2][2], const u16* __restrict__ A, int lda, const u16* __restrict__ B, int ldb, int K, u16* sm) {
;     ...
;     for (int ks = 0; ks < 4; ks++) {
;       const int ca = ((ks * 2 + hh) ^ xa) << 4, cb = ((ks * 2 + hh) ^ xb) << 4;
;       const bf16x8 fa0 = *(const bf16x8*)(st + baseA + ca);
;       const bf16x8 fa1 = *(const bf16x8*)(st + baseA + 4096 + ca);
;       const bf16x8 fb0 = *(const bf16x8*)(st + baseB + cb);
;       const bf16x8 fb1 = *(const bf16x8*)(st + baseB + 4096 + cb);
;       acc[0][0] = MFMA32(fa0, fb0, acc[0][0]); acc[0][1] = MFMA32(fa0, fb1, acc[0][1]);
;       acc[1][0] = MFMA32(fa1, fb0, acc[1][0]); acc[1][1] = MFMA32(fa1, fb1, acc[1][1]);
;     }
;     asm volatile("s_waitcnt vmcnt(0)" ::: "memory");
;     __syncthreads();
.Lkl7_last:
	v_add_u32_e32 v188, s36, v166
	v_add3_u32 v189, s36, v167, v66
	v_add_u32_e32 v180, v188, v168
	v_add_u32_e32 v184, v189, v168
	ds_read_b128 v[172:175], v180
	ds_read_b128 v[176:179], v184 offset:16384
	ds_read_b128 v[180:183], v180 offset:4096
	ds_read_b128 v[184:187], v184 offset:20480
	v_add_u32_e32 v248, v188, v169
	v_add_u32_e32 v252, v189, v169
	ds_read_b128 v[240:243], v248
	ds_read_b128 v[244:247], v252 offset:16384
	ds_read_b128 v[248:251], v248 offset:4096
	ds_read_b128 v[252:255], v252 offset:20480
	s_waitcnt lgkmcnt(4)
	v_mfma_f32_32x32x16_bf16 v[34:49], v[180:183], v[176:179], v[34:49]
	v_mfma_f32_32x32x16_bf16 v[50:65], v[180:183], v[184:187], v[50:65]
	v_mfma_f32_32x32x16_bf16 v[2:17], v[172:175], v[176:179], v[2:17]
	v_mfma_f32_32x32x16_bf16 v[18:33], v[172:175], v[184:187], v[18:33]
	v_add_u32_e32 v180, v188, v170
	v_add_u32_e32 v184, v189, v170
	ds_read_b128 v[172:175], v180
	ds_read_b128 v[176:179], v184 offset:16384
	ds_read_b128 v[180:183], v180 offset:4096
	ds_read_b128 v[184:187], v184 offset:20480
	s_waitcnt lgkmcnt(4)
	v_mfma_f32_32x32x16_bf16 v[34:49], v[248:251], v[244:247], v[34:49]
	v_mfma_f32_32x32x16_bf16 v[50:65], v[248:251], v[252:255], v[50:65]
	v_mfma_f32_32x32x16_bf16 v[2:17], v[240:243], v[244:247], v[2:17]
	v_mfma_f32_32x32x16_bf16 v[18:33], v[240:243], v[252:255], v[18:33]
	v_add_u32_e32 v248, v188, v171
	v_add_u32_e32 v252, v189, v171
	ds_read_b128 v[240:243], v248
	ds_read_b128 v[244:247], v252 offset:16384
	ds_read_b128 v[248:251], v248 offset:4096
	ds_read_b128 v[252:255], v252 offset:20480
	s_waitcnt lgkmcnt(4)
	v_mfma_f32_32x32x16_bf16 v[34:49], v[180:183], v[176:179], v[34:49]
	v_mfma_f32_32x32x16_bf16 v[50:65], v[180:183], v[184:187], v[50:65]
	v_mfma_f32_32x32x16_bf16 v[2:17], v[172:175], v[176:179], v[2:17]
	v_mfma_f32_32x32x16_bf16 v[18:33], v[172:175], v[184:187], v[18:33]
	s_add_i32 s38, s38, 1
	s_waitcnt vmcnt(0) lgkmcnt(0)
	s_barrier
	v_mfma_f32_32x32x16_bf16 v[2:17], v[240:243], v[244:247], v[2:17]
	v_mfma_f32_32x32x16_bf16 v[18:33], v[240:243], v[252:255], v[18:33]
	v_mfma_f32_32x32x16_bf16 v[34:49], v[248:251], v[244:247], v[34:49]
	v_mfma_f32_32x32x16_bf16 v[50:65], v[248:251], v[252:255], v[50:65]
	s_setprio 0
	s_branch .LBB0_4732

; DI int tidx() { int t = threadIdx.x; asm volatile("" : "+v"(t)); return t; }
; #define GAS __attribute__((address_space(1)))
; DI void gemm_stage(const u16* __restrict__ A, int lda, const u16* __restrict__ B, int ldb, int kt, char* sbuf) {
;   const int tid = tidx(), lane = tid & 63, wave = __builtin_amdgcn_readfirstlane(tid >> 6);
;   const int pp = lane >> 4, pos = lane & 15;
; #pragma unroll
;   for (int i = 0; i < 4; i++) {
;     const int blk = i * 4 + wave;
;     const int p = blk * 4 + pp;
;     const int row = 2 * p + (pos >> 3), c8 = (pos & 7) ^ (p & 7);
;     const u16* ga = A + (size_t)row * lda + kt * 64 + c8 * 8;
;     const u16* gb = B + (size_t)row * ldb + kt * 64 + c8 * 8;
;     __builtin_amdgcn_global_load_lds((const GAS void*)ga, (__attribute__((address_space(3))) void*)(sbuf + blk * 1024), 16, 0, 0);
;     __builtin_amdgcn_global_load_lds((const GAS void*)gb, (__attribute__((address_space(3))) void*)(sbuf + 16384 + blk * 1024), 16, 0, 0);
;   }
.LBB0_4992:
	s_setprio 1
	s_mov_b32 s30, 0
	s_mov_b32 s33, 0
	v_readfirstlane_b32 s34, v202
	v_bfe_u32 v238, v202, 4, 2
	v_bfe_u32 v239, v202, 3, 1
	s_ashr_i32 s34, s34, 6
	s_lshl_b32 s31, s34, 3
	v_lshlrev_b32_e32 v188, 1, v238
	v_or3_b32 v188, s31, v188, v239
	v_lshl_or_b32 v238, s34, 2, v238
	v_bitop3_b32 v238, v238, 7, v202 bitop3:0x48
	v_lshlrev_b32_e32 v238, 4, v238
	v_mul_u32_u24_e32 v188, 0x1600, v188
	v_add_u32_e32 v238, v188, v238
	v_add_u32_e32 v239, 0x2c000, v238
	s_lshl_b32 s34, s34, 10
	s_add_u32 s14, s10, 0x58000
	s_addc_u32 s15, s11, 0
	s_add_u32 s16, s12, 0x58000
	s_addc_u32 s17, s13, 0

; #define MFMA32(a, b, c) __builtin_amdgcn_mfma_f32_32x32x16_bf16((a), (b), (c), 0, 0, 0)
; DI void gemm_main(f32x16 (&acc)[2][2], const u16* __restrict__ A, int lda, const u16* __restrict__ B, int ldb, int K, u16* sm) {
;     ...
;     for (int ks = 0; ks < 4; ks++) {
;       const int ca = ((ks * 2 + hh) ^ xa) << 4, cb = ((ks * 2 + hh) ^ xb) << 4;
;       const bf16x8 fa0 = *(const bf16x8*)(st + baseA + ca);
;       const bf16x8 fa1 = *(const bf16x8*)(st + baseA + 4096 + ca);
;       const bf16x8 fb0 = *(const bf16x8*)(st + baseB + cb);
;       const bf16x8 fb1 = *(const bf16x8*)(st + baseB + 4096 + cb);
;       acc[0][0] = MFMA32(fa0, fb0, acc[0][0]); acc[0][1] = MFMA32(fa0, fb1, acc[0][1]);
;       acc[1][0] = MFMA32(fa1, fb0, acc[1][0]); acc[1][1] = MFMA32(fa1, fb1, acc[1][1]);
;     }
;     asm volatile("s_waitcnt vmcnt(0)" ::: "memory");
;     __syncthreads();
.Lkl9_last:
	v_add_u32_e32 v188, s30, v166
	v_add3_u32 v189, s30, v167, v66
	v_add_u32_e32 v180, v188, v168
	v_add_u32_e32 v184, v189, v168
	ds_read_b128 v[172:175], v180
	ds_read_b128 v[176:179], v184 offset:16384
	ds_read_b128 v[180:183], v180 offset:4096
	ds_read_b128 v[184:187], v184 offset:20480
	v_add_u32_e32 v248, v188, v169
	v_add_u32_e32 v252, v189, v169
	ds_read_b128 v[240:243], v248
	ds_read_b128 v[244:247], v252 offset:16384
	ds_read_b128 v[248:251], v248 offset:4096
	ds_read_b128 v[252:255], v252 offset:20480
	s_waitcnt lgkmcnt(4)
	v_mfma_f32_32x32x16_bf16 v[34:49], v[180:183], v[176:179], v[34:49]
	v_mfma_f32_32x32x16_bf16 v[18:33], v[180:183], v[184:187], v[18:33]
	v_mfma_f32_32x32x16_bf16 v[2:17], v[172:175], v[176:179], v[2:17]
	v_mfma_f32_32x32x16_bf16 v[50:65], v[172:175], v[184:187], v[50:65]
	v_add_u32_e32 v180, v188, v170
	v_add_u32_e32 v184, v189, v170
	ds_read_b128 v[172:175], v180
	ds_read_b128 v[176:179], v184 offset:16384
	ds_read_b128 v[180:183], v180 offset:4096
	ds_read_b128 v[184:187], v184 offset:20480
	s_waitcnt lgkmcnt(4)
	v_mfma_f32_32x32x16_bf16 v[34:49], v[248:251], v[244:247], v[34:49]
	v_mfma_f32_32x32x16_bf16 v[18:33], v[248:251], v[252:255], v[18:33]
	v_mfma_f32_32x32x16_bf16 v[2:17], v[240:243], v[244:247], v[2:17]
	v_mfma_f32_32x32x16_bf16 v[50:65], v[240:243], v[252:255], v[50:65]
	v_add_u32_e32 v248, v188, v171
	v_add_u32_e32 v252, v189, v171
	ds_read_b128 v[240:243], v248
	ds_read_b128 v[244:247], v252 offset:16384
	ds_read_b128 v[248:251], v248 offset:4096
	ds_read_b128 v[252:255], v252 offset:20480
	s_waitcnt lgkmcnt(4)
	v_mfma_f32_32x32x16_bf16 v[34:49], v[180:183], v[176:179], v[34:49]
	v_mfma_f32_32x32x16_bf16 v[18:33], v[180:183], v[184:187], v[18:33]
	v_mfma_f32_32x32x16_bf16 v[2:17], v[172:175], v[176:179], v[2:17]
	v_mfma_f32_32x32x16_bf16 v[50:65], v[172:175], v[184:187], v[50:65]
	s_add_i32 s33, s33, 1
	s_waitcnt vmcnt(0) lgkmcnt(0)
	s_barrier
	v_mfma_f32_32x32x16_bf16 v[2:17], v[240:243], v[244:247], v[2:17]
	v_mfma_f32_32x32x16_bf16 v[50:65], v[240:243], v[252:255], v[50:65]
	v_mfma_f32_32x32x16_bf16 v[34:49], v[248:251], v[244:247], v[34:49]
	v_mfma_f32_32x32x16_bf16 v[18:33], v[248:251], v[252:255], v[18:33]
	s_setprio 0
	s_branch .LBB0_4996

; DI f32x16 zero16() { f32x16 z; for (int i = 0; i < 16; i++) z[i] = 0.f; return z; }
; #define DA_FETCH(T) { const int ktn_ = min((T), nkt - 1); \
;       _Pragma("unroll") for (int i = 0; i < 2; i++) rk[i] = *(const u32x4*)(Kbase + (size_t)(ktn_ * 64 + i * 32) * 64); \
;       _Pragma("unroll") for (int i = 0; i < 4; i++) rv[i] = *(const u32x4*)(Vbase + (size_t)ktn_ * 8192 + (size_t)(i * 32) * 64); }
; DI void da_item(const Params& P, int layer, int b, int h, int qt, char* mb, char* smem) {
;     ...
;   const int krow_l = tid >> 3, kch = (tid & 7) * 8;
; #pragma unroll 1
;   for (int c = 0; c < 2; c++) {
; #pragma unroll
;     for (int ks = 0; ks < 4; ks++) *(bf16x8*)(sQw + r * KS_ + ks * 16 + hh * 8) = *(const bf16x8*)(Qd + tokq * 512 + h * 128 + c * 64 + ks * 16 + hh * 8);
;     f32x16 o[4] = {zero16(), zero16(), zero16(), zero16()};
;     float m = -INFINITY, l = 0.f;
;     const u16* Kbase = Kd + ((size_t)(((b * 4 + h) * 2 + c)) * L_ + krow_l) * 64 + kch;
;     const u16* Vbase = Vt + ((size_t)((b * 4 + h) * 128) * 128 + krow_l) * 64 + kch;
;     u32x4 rk[2], rv[4];
; #pragma unroll
;     for (int i = 0; i < 2; i++) rk[i] = *(const u32x4*)(Kbase + (size_t)(i * 32) * 64);
; #pragma unroll
;     for (int i = 0; i < 4; i++) rv[i] = *(const u32x4*)(Vbase + (size_t)(i * 32) * 64);
;     ...
;     __syncthreads();
;     DA_STAGE(0)
;     DA_FETCH(1)
;     __syncthreads();
.LBB0_8076:
	s_lshl_b32 s10, s29, 7
	v_lshl_add_u64 v[16:17], v[146:147], 0, s[10:11]
	global_load_dwordx4 v[4:7], v[16:17], off
	global_load_dwordx4 v[8:11], v[16:17], off offset:32
	global_load_dwordx4 v[12:15], v[16:17], off offset:64
	s_nop 0
	global_load_dwordx4 v[16:19], v[16:17], off offset:96
	s_lshl_b32 s10, s29, 13
	s_or_b32 s10, s10, s22
	v_lshl_add_u64 v[20:21], s[10:11], 0, v[144:145]
	v_lshlrev_b64 v[20:21], 7, v[20:21]
	v_lshl_add_u64 v[182:183], v[148:149], 0, v[20:21]
	global_load_dwordx4 v[20:23], v[182:183], off
	v_add_co_u32_e32 v24, vcc, s36, v182
	v_lshl_add_u64 v[44:45], v[182:183], 0, s[24:25]
	s_nop 0
	v_addc_co_u32_e32 v25, vcc, 0, v183, vcc
	global_load_dwordx4 v[24:27], v[24:25], off
	s_nop 0
	global_load_dwordx4 v[28:31], v[150:151], off
	global_load_dwordx4 v[32:35], v[156:157], off
	global_load_dwordx4 v[36:39], v[158:159], off
	global_load_dwordx4 v[40:43], v[160:161], off
	v_lshl_add_u64 v[46:47], v[182:183], 0, s[26:27]
	v_add_u32_e32 v3, v214, v219
	s_xor_b64 s[28:29], s[4:5], -1
	v_mov_b32_e32 v227, 0xff800000
	v_mov_b32_e32 v226, 0
	s_movk_i32 s10, 0xbf
	v_mov_b32_e32 v225, v223
	s_mov_b32 s30, 0
	s_waitcnt vmcnt(9)
	ds_write_b128 v213, v[4:7] offset:54272
	s_waitcnt vmcnt(8)
	ds_write_b128 v213, v[8:11] offset:54304
	s_waitcnt vmcnt(7)
	ds_write_b128 v213, v[12:15] offset:54336
	s_waitcnt vmcnt(6)
	ds_write_b128 v213, v[16:19] offset:54368
	v_mov_b32_e32 v240, v4
	v_mov_b32_e32 v241, v5
	v_mov_b32_e32 v242, v6
	v_mov_b32_e32 v243, v7
	v_mov_b32_e32 v244, v8
	v_mov_b32_e32 v245, v9
	v_mov_b32_e32 v246, v10
	v_mov_b32_e32 v247, v11
	v_mov_b32_e32 v248, v12
	v_mov_b32_e32 v249, v13
	v_mov_b32_e32 v250, v14
	v_mov_b32_e32 v251, v15
	v_mov_b32_e32 v252, v16
	v_mov_b32_e32 v253, v17
	v_mov_b32_e32 v254, v18
	v_mov_b32_e32 v255, v19
	s_waitcnt lgkmcnt(0)
	s_barrier
	global_load_dwordx4 v[114:117], v[44:45], off
	global_load_dwordx4 v[118:121], v[46:47], off
	global_load_dwordx4 v[122:125], v[152:153], off
	global_load_dwordx4 v[126:129], v[162:163], off
	global_load_dwordx4 v[130:133], v[164:165], off
	global_load_dwordx4 v[134:137], v[166:167], off
	s_waitcnt vmcnt(11)
	ds_write_b128 v3, v[20:23]
	s_waitcnt vmcnt(10)
	ds_write_b128 v3, v[24:27] offset:4608
	v_add_u32_e32 v3, v214, v220
	v_add_u32_e32 v4, 0x4800, v3
	s_waitcnt vmcnt(9)
	ds_write2_b64 v4, v[28:29], v[30:31] offset1:1
	v_add_u32_e32 v4, 0x5900, v3
	s_waitcnt vmcnt(8)
	ds_write2_b64 v4, v[32:33], v[34:35] offset1:1
	v_add_u32_e32 v4, 0x6a00, v3
	v_add_u32_e32 v3, 0x7b00, v3
	v_mov_b32_e32 v16, v2
	v_mov_b32_e32 v17, v2
	s_waitcnt vmcnt(7)
	ds_write2_b64 v4, v[36:37], v[38:39] offset1:1
	s_waitcnt vmcnt(6)
	ds_write2_b64 v3, v[40:41], v[42:43] offset1:1
	v_mov_b32_e32 v3, v2
	v_mov_b32_e32 v4, v2
	v_mov_b32_e32 v5, v2
	v_mov_b32_e32 v6, v2
	v_mov_b32_e32 v7, v2
	v_mov_b32_e32 v8, v2
	v_mov_b32_e32 v9, v2
	v_mov_b32_e32 v10, v2
	v_mov_b32_e32 v11, v2
	v_mov_b32_e32 v12, v2
	v_mov_b32_e32 v13, v2
	v_mov_b32_e32 v14, v2
	v_mov_b32_e32 v15, v2
	v_mov_b64_e32 v[32:33], v[16:17]
	v_mov_b64_e32 v[48:49], v[16:17]
	v_mov_b64_e32 v[64:65], v[16:17]
	v_mov_b64_e32 v[80:81], v[16:17]
	v_mov_b64_e32 v[30:31], v[14:15]
	v_mov_b64_e32 v[28:29], v[12:13]
	v_mov_b64_e32 v[26:27], v[10:11]
	v_mov_b64_e32 v[24:25], v[8:9]
	v_mov_b64_e32 v[22:23], v[6:7]
	v_mov_b64_e32 v[20:21], v[4:5]
	v_mov_b64_e32 v[18:19], v[2:3]
	v_mov_b64_e32 v[46:47], v[14:15]
	v_mov_b64_e32 v[44:45], v[12:13]
	v_mov_b64_e32 v[42:43], v[10:11]
	v_mov_b64_e32 v[40:41], v[8:9]
	v_mov_b64_e32 v[38:39], v[6:7]
	v_mov_b64_e32 v[36:37], v[4:5]
	v_mov_b64_e32 v[34:35], v[2:3]
	v_mov_b64_e32 v[62:63], v[14:15]
	v_mov_b64_e32 v[60:61], v[12:13]
	v_mov_b64_e32 v[58:59], v[10:11]
	v_mov_b64_e32 v[56:57], v[8:9]
	v_mov_b64_e32 v[54:55], v[6:7]
	v_mov_b64_e32 v[52:53], v[4:5]
	v_mov_b64_e32 v[50:51], v[2:3]
	v_mov_b64_e32 v[78:79], v[14:15]
	v_mov_b64_e32 v[76:77], v[12:13]
	v_mov_b64_e32 v[74:75], v[10:11]
	v_mov_b64_e32 v[72:73], v[8:9]
	v_mov_b64_e32 v[70:71], v[6:7]
	v_mov_b64_e32 v[68:69], v[4:5]
	v_mov_b64_e32 v[66:67], v[2:3]
	s_waitcnt lgkmcnt(0)
	s_barrier
	s_add_i32 s43, s30, 1
	s_cmp_ge_u32 s43, s41
	s_cbranch_scc1 .LBB0_8079
	s_branch .LBB0_8078

; #define MFMA32(a, b, c) __builtin_amdgcn_mfma_f32_32x32x16_bf16((a), (b), (c), 0, 0, 0)
; DI int crow(int i, int hh) { return (i & 3) + 8 * (i >> 2) + 4 * hh; }
; DI f32x16 zero16() { f32x16 z; for (int i = 0; i < 16; i++) z[i] = 0.f; return z; }
; #define DA_FETCH(T) { const int ktn_ = min((T), nkt - 1); \
;       _Pragma("unroll") for (int i = 0; i < 2; i++) rk[i] = *(const u32x4*)(Kbase + (size_t)(ktn_ * 64 + i * 32) * 64); \
;       _Pragma("unroll") for (int i = 0; i < 4; i++) rv[i] = *(const u32x4*)(Vbase + (size_t)ktn_ * 8192 + (size_t)(i * 32) * 64); }
; DI void da_item(const Params& P, int layer, int b, int h, int qt, char* mb, char* smem) {
;     ...
;     for (int kt = 0; kt < nkt; kt++) {
;       const u16* sK = sK0 + (kt & 1) * 64 * KS_;
;       const u16* sV = sV0 + (kt & 1) * 128 * VS_;
;       if (kt + 1 < nkt) { DA_STAGE((kt + 1) & 1) }
;       DA_FETCH(kt + 2)
;       if (kt * 64 <= qw + 31) {
;         f32x16 s[2];
; #pragma unroll
;         for (int kb = 0; kb < 2; kb++) {
;           s[kb] = zero16();
; #pragma unroll
;           for (int ks = 0; ks < 4; ks++) {
;             const bf16x8 kf = *(const bf16x8*)(sK + (kb * 32 + r) * KS_ + ks * 16 + hh * 8);
;             const bf16x8 qf = *(const bf16x8*)(sQw + r * KS_ + ks * 16 + hh * 8);
;             s[kb] = MFMA32(kf, qf, s[kb]);
;           }
;         }
;         const bool nearb = (kt * 64 + 63 + 128 > qw);
;         float mx = -INFINITY;
;         if (nearb) {
; #pragma unroll
;           for (int kb = 0; kb < 2; kb++)
; #pragma unroll
;             for (int i = 0; i < 16; i++) {
;               const int dist = qp - (kt * 64 + kb * 32 + crow(i, hh));
;               const float bv = sbias[min(max(dist, 0), 128)];
;               float t = s[kb][i] * SC + bv;
;               t = (dist >= 0) ? t : -INFINITY;
;               s[kb][i] = t; mx = fmaxf(mx, t);
;               if ((i & 7) == 7) __builtin_amdgcn_sched_barrier(0);
;             }
;         } else {
.LBB0_8079:
	s_add_i32 s4, s30, 2
	s_min_i32 s4, s4, s23
	s_lshl_b32 s44, s4, 6
	s_ashr_i32 s45, s44, 31
	s_lshl_b64 s[46:47], s[44:45], 7
	s_or_b32 s44, s44, 32
	s_ashr_i32 s45, s44, 31
	s_ashr_i32 s5, s4, 31
	v_lshl_add_u64 v[4:5], v[182:183], 0, s[46:47]
	s_lshl_b64 s[44:45], s[44:45], 7
	s_lshl_b64 s[4:5], s[4:5], 14
	v_lshl_add_u64 v[6:7], v[182:183], 0, s[44:45]
	global_load_dwordx4 v[114:117], v[4:5], off
	global_load_dwordx4 v[118:121], v[6:7], off
	v_lshl_add_u64 v[4:5], v[150:151], 0, s[4:5]
	v_add_co_u32_e32 v6, vcc, 0x1000, v4
	s_add_i32 s4, s10, 0xffffff41
	s_nop 0
	v_addc_co_u32_e32 v7, vcc, 0, v5, vcc
	global_load_dwordx4 v[122:125], v[4:5], off
	global_load_dwordx4 v[126:129], v[6:7], off
	v_add_co_u32_e32 v6, vcc, 0x2000, v4
	s_nop 1
	v_addc_co_u32_e32 v7, vcc, 0, v5, vcc
	v_add_co_u32_e32 v4, vcc, 0x3000, v4
	s_nop 1
	v_addc_co_u32_e32 v5, vcc, 0, v5, vcc
	global_load_dwordx4 v[130:133], v[6:7], off
	global_load_dwordx4 v[134:137], v[4:5], off
	v_cmp_le_i32_e32 vcc, s4, v215
	s_and_saveexec_b64 s[4:5], vcc
	s_cbranch_execz .LBB0_8087
	s_and_b32 s44, s30, 1
	s_mul_i32 s30, s44, 0x2400
	v_add_u32_e32 v3, s30, v216
	v_add_u32_e32 v16, v3, v212
	ds_read_b128 v[4:7], v16
	ds_read_b128 v[82:85], v16 offset:32
	v_add_u32_e32 v3, v3, v221
	v_cmp_le_i32_e32 vcc, s10, v211
	s_waitcnt lgkmcnt(1)
	v_mfma_f32_32x32x16_bf16 v[98:113], v[4:7], v[240:243], 0
	s_waitcnt lgkmcnt(0)
	v_mfma_f32_32x32x16_bf16 v[98:113], v[82:85], v[244:247], v[98:113]
	ds_read_b128 v[4:7], v16 offset:64
	ds_read_b128 v[82:85], v16 offset:96
	s_waitcnt lgkmcnt(1)
	v_mfma_f32_32x32x16_bf16 v[98:113], v[4:7], v[248:251], v[98:113]
	ds_read_b128 v[4:7], v3
	ds_read_b128 v[188:191], v3 offset:32
	s_waitcnt lgkmcnt(2)
	v_mfma_f32_32x32x16_bf16 v[98:113], v[82:85], v[252:255], v[98:113]
	s_waitcnt lgkmcnt(1)
	v_mfma_f32_32x32x16_bf16 v[82:97], v[4:7], v[240:243], 0
	ds_read_b128 v[4:7], v3 offset:64
	ds_read_b128 v[232:235], v3 offset:96
	s_waitcnt lgkmcnt(2)
	v_mfma_f32_32x32x16_bf16 v[82:97], v[188:191], v[244:247], v[82:97]
	s_waitcnt lgkmcnt(1)
	v_mfma_f32_32x32x16_bf16 v[82:97], v[4:7], v[248:251], v[82:97]
	s_waitcnt lgkmcnt(0)
	v_mfma_f32_32x32x16_bf16 v[82:97], v[232:235], v[252:255], v[82:97]
	s_and_saveexec_b64 s[30:31], vcc
	s_xor_b64 s[30:31], exec, s[30:31]
	s_cbranch_execz .LBB0_8082
	v_pk_fma_f32 v[4:5], v[98:99], s[20:21], v[138:139] op_sel_hi:[1,0,1]
	v_pk_fma_f32 v[6:7], v[100:101], s[20:21], v[138:139] op_sel_hi:[1,0,1]
	v_max3_f32 v3, v4, s37, v5
	v_max3_f32 v3, v3, v6, v7
	v_pk_fma_f32 v[8:9], v[102:103], s[20:21], v[138:139] op_sel_hi:[1,0,1]
	v_pk_fma_f32 v[10:11], v[104:105], s[20:21], v[138:139] op_sel_hi:[1,0,1]
	v_max3_f32 v3, v3, v8, v9
	v_max3_f32 v3, v3, v10, v11
	v_pk_fma_f32 v[12:13], v[106:107], s[20:21], v[138:139] op_sel_hi:[1,0,1]
	v_pk_fma_f32 v[14:15], v[108:109], s[20:21], v[138:139] op_sel_hi:[1,0,1]
	v_max3_f32 v3, v3, v12, v13
	v_max3_f32 v3, v3, v14, v15
	v_pk_fma_f32 v[16:17], v[110:111], s[20:21], v[138:139] op_sel_hi:[1,0,1]
	v_pk_fma_f32 v[184:185], v[112:113], s[20:21], v[138:139] op_sel_hi:[1,0,1]
	v_max3_f32 v3, v3, v16, v17
	v_max3_f32 v3, v3, v184, v185
	v_pk_fma_f32 v[186:187], v[82:83], s[20:21], v[138:139] op_sel_hi:[1,0,1]
	v_pk_fma_f32 v[188:189], v[84:85], s[20:21], v[138:139] op_sel_hi:[1,0,1]
	v_max3_f32 v3, v3, v186, v187
	v_max3_f32 v3, v3, v188, v189
	v_pk_fma_f32 v[190:191], v[86:87], s[20:21], v[138:139] op_sel_hi:[1,0,1]
	v_pk_fma_f32 v[192:193], v[88:89], s[20:21], v[138:139] op_sel_hi:[1,0,1]
	v_max3_f32 v3, v3, v190, v191
	v_max3_f32 v3, v3, v192, v193
	v_pk_fma_f32 v[200:201], v[90:91], s[20:21], v[138:139] op_sel_hi:[1,0,1]
	v_pk_fma_f32 v[198:199], v[92:93], s[20:21], v[138:139] op_sel_hi:[1,0,1]
	v_max3_f32 v3, v3, v200, v201
	v_max3_f32 v3, v3, v198, v199
	v_pk_fma_f32 v[196:197], v[94:95], s[20:21], v[138:139] op_sel_hi:[1,0,1]
	v_pk_fma_f32 v[194:195], v[96:97], s[20:21], v[138:139] op_sel_hi:[1,0,1]
	v_max3_f32 v3, v3, v196, v197
	v_max3_f32 v3, v3, v194, v195
